# per-unit staging offsets stashed in LDS instead of recomputed (up-proj, in-proj GEMM), HGRN LDS reads pipelined, sample-attention staging pipelined
# speedup vs baseline: 1.0116x; 1.0056x over previous
.LBB0_776:
	v_add_u32_e32 v0, s60, v0
	v_ashrrev_i32_e32 v2, 31, v0
	v_lshrrev_b32_e32 v2, 26, v2
	v_lshlrev_b32_e32 v1, 4, v0
	v_add_u32_e32 v2, v0, v2
	v_bfe_i32 v0, v0, 27, 1
	v_lshrrev_b32_e32 v0, 22, v0
	v_add_u32_e32 v0, v1, v0
	v_and_b32_e32 v0, 0xfffffc00, v0
	v_sub_u32_e32 v0, v1, v0
	v_lshrrev_b32_e32 v3, 4, v0
	v_bitop3_b32 v0, v3, v0, 32 bitop3:0x6c
	v_ashrrev_i32_e32 v4, 31, v0
	v_ashrrev_i32_e32 v2, 6, v2
	v_lshrrev_b32_e32 v4, 26, v4
	v_lshlrev_b32_e32 v3, 3, v2
	v_add_u32_e32 v4, v0, v4
	v_and_b32_e32 v3, -16, v3
	v_ashrrev_i32_e32 v5, 6, v4
	v_and_b32_e32 v4, 0xc0, v4
	v_add_u32_e32 v3, v5, v3
	v_sub_u32_e32 v0, v0, v4
	v_mov_b32_e32 v7, 1
	v_lshlrev_b32_e32 v2, 5, v2
	v_ashrrev_i16_sdwa v0, v7, sext(v0) dst_sel:DWORD dst_unused:UNUSED_PAD src0_sel:DWORD src1_sel:BYTE_0
	v_lshlrev_b32_e32 v4, 1, v3
	v_lshrrev_b32_e32 v6, 2, v3
	v_and_b32_e32 v5, 3, v5
	s_mov_b32 s2, 0x1fffe0
	v_and_b32_e32 v2, 32, v2
	v_bfe_i32 v0, v0, 0, 16
	v_and_b32_e32 v4, 24, v4
	v_and_b32_e32 v6, 4, v6
	v_and_or_b32 v5, v3, s2, v5
	v_or3_b32 v4, v5, v6, v4
	v_add_lshl_u32 v0, v2, v0, 1
	v_lshl_add_u32 v122, v3, 11, v0
	v_lshl_add_u32 v120, v4, 11, v0
	v_add_u32_e32 v0, 0x2000, v1
	v_ashrrev_i32_e32 v1, 31, v0
	v_lshrrev_b32_e32 v1, 22, v1
	v_add_u32_e32 v1, v0, v1
	v_ashrrev_i32_e32 v1, 10, v1
	v_mul_i32_i24_e32 v2, 0x400, v1
	v_sub_u32_e32 v0, v0, v2
	v_lshrrev_b32_e32 v2, 4, v0
	v_bitop3_b32 v0, v2, v0, 32 bitop3:0x6c
	v_ashrrev_i32_e32 v3, 31, v0
	v_lshrrev_b32_e32 v3, 26, v3
	v_lshlrev_b32_e32 v2, 3, v1
	v_add_u32_e32 v3, v0, v3
	v_and_b32_e32 v2, -16, v2
	v_ashrrev_i32_e32 v4, 6, v3
	v_and_b32_e32 v3, 0xc0, v3
	v_add_u32_e32 v2, v4, v2
	v_sub_u32_e32 v0, v0, v3
	v_lshlrev_b32_e32 v1, 5, v1
	v_ashrrev_i16_sdwa v0, v7, sext(v0) dst_sel:DWORD dst_unused:UNUSED_PAD src0_sel:DWORD src1_sel:BYTE_0
	v_lshlrev_b32_e32 v3, 1, v2
	v_lshrrev_b32_e32 v5, 2, v2
	v_and_b32_e32 v4, 3, v4
	v_and_b32_e32 v1, 32, v1
	v_bfe_i32 v0, v0, 0, 16
	v_and_b32_e32 v3, 24, v3
	v_and_b32_e32 v5, 4, v5
	v_and_or_b32 v4, v2, s2, v4
	v_or3_b32 v3, v4, v5, v3
	v_add_lshl_u32 v0, v1, v0, 1
	v_lshl_add_u32 v124, v2, 11, v0
	v_lshl_add_u32 v160, v3, 11, v0
	v_mbcnt_lo_u32_b32 v5, -1, 0
	v_mbcnt_hi_u32_b32 v5, -1, v5
	v_add_u32_e32 v5, s60, v5
	v_lshlrev_b32_e32 v5, 2, v5
	v_add_u32_e32 v5, 0x24000, v5
	ds_write_b32 v5, v122
	ds_write_b32 v5, v120 offset:2048
	ds_write_b32 v5, v124 offset:4096
	ds_write_b32 v5, v160 offset:6144
	s_ashr_i32 s86, s18, 8
	s_lshl_b32 s87, s19, 10
	s_ashr_i32 s9, s8, 31
	s_lshl_b64 s[24:25], s[4:5], 19
	s_lshl_b64 s[22:23], s[8:9], 19
	s_add_u32 s22, s82, s22
	s_addc_u32 s23, s83, s23
	s_add_i32 s88, s87, 0
	s_add_i32 m0, s88, 0x10000
	v_mov_b32_e32 v121, v161
	global_load_lds_dwordx4 v120, s[22:23]
	s_add_i32 m0, s88, 0x12000
	s_add_u32 s36, s22, 0x40000
	global_load_lds_dwordx4 v160, s[22:23]
	s_addc_u32 s37, s23, 0
	s_add_i32 m0, s88, 0x14000
	v_mov_b32_e32 v123, v161
	global_load_lds_dwordx4 v120, s[36:37]
	s_add_i32 m0, s88, 0x16000
	s_add_u32 s24, s84, s24
	s_addc_u32 s25, s85, s25
	s_add_i32 s89, s88, 0x2000
	global_load_lds_dwordx4 v160, s[36:37]
	s_mov_b32 m0, s88
	s_add_u32 s36, s24, 0x40000
	global_load_lds_dwordx4 v122, s[24:25]
	s_mov_b32 m0, s89
	s_addc_u32 s37, s25, 0
	s_add_i32 s90, s88, 0x4000
	global_load_lds_dwordx4 v124, s[24:25]
	s_mov_b32 m0, s90
	s_add_i32 s91, s88, 0x6000
	global_load_lds_dwordx4 v122, s[36:37]
	s_mov_b32 m0, s91
	s_cmp_eq_u32 s86, 1
	global_load_lds_dwordx4 v124, s[36:37]
	s_cselect_b64 s[36:37], -1, 0
	v_mov_b32_e32 v125, v161
	v_writelane_b32 v255, s36, 4
	v_lshl_add_u64 v[6:7], s[22:23], 0, v[120:121]
	v_lshl_add_u64 v[2:3], s[22:23], 0, v[160:161]
	v_lshl_add_u64 v[0:1], s[24:25], 0, v[122:123]
	v_writelane_b32 v255, s37, 5
	s_cmp_lg_u32 s86, 1
	v_lshl_add_u64 v[4:5], s[24:25], 0, v[124:125]
	s_mov_b32 s2, 0x10000
	v_readlane_b32 s42, v254, 58
	s_cbranch_scc1 .LBB0_778
	s_barrier

.LBB0_779:
	v_add_u32_e32 v0, s60, v0
	v_lshlrev_b32_e32 v0, 2, v0
	v_add_u32_e32 v0, 0x24000, v0
	ds_read_b32 v122, v0
	ds_read_b32 v120, v0 offset:2048
	ds_read_b32 v124, v0 offset:4096
	ds_read_b32 v160, v0 offset:6144
	s_waitcnt lgkmcnt(0)
	s_mov_b64 s[4:5], 0

.LBB0_984:
	s_nop 10
	ds_write_b128 v112, v[32:35] offset:50176
	ds_write_b128 v112, v[36:39] offset:50208
	ds_write_b128 v112, v[40:43] offset:50240
	ds_write_b128 v112, v[44:47] offset:50272
	ds_read_b64_tr_b16 v[32:33], v113 offset:27648
	ds_read_b64_tr_b16 v[34:35], v113 offset:28928
	ds_read_b64_tr_b16 v[36:37], v114 offset:37888
	ds_read_b64_tr_b16 v[38:39], v114 offset:39168
	ds_read_b64_tr_b16 v[128:129], v113 offset:32768
	ds_read_b64_tr_b16 v[130:131], v113 offset:34048
	ds_read_b64_tr_b16 v[40:41], v114 offset:43008
	ds_read_b64_tr_b16 v[42:43], v114 offset:44288
	v_lshlrev_b32_e32 v78, 16, v71
	v_and_b32_e32 v79, 0xffff0000, v71
	s_add_i32 s87, s87, 1
	s_cmp_lg_u32 s87, 64
	v_add_u32_e32 v144, s81, v105
	s_waitcnt lgkmcnt(4)
	v_mfma_f32_32x32x16_bf16 v[16:31], v[32:35], v[36:39], v[16:31]
	ds_read_b64_tr_b16 v[132:133], v113 offset:27712
	ds_read_b64_tr_b16 v[134:135], v113 offset:28992
	s_waitcnt lgkmcnt(2)
	v_mfma_f32_32x32x16_bf16 v[16:31], v[128:131], v[40:43], v[16:31]
	ds_read_b64_tr_b16 v[136:137], v113 offset:32832
	ds_read_b64_tr_b16 v[138:139], v113 offset:34112
	ds_read_b128 v[148:151], v144 offset:18432
	ds_read_b128 v[152:155], v144 offset:18464
	ds_read_b128 v[156:159], v144 offset:18496
	ds_read_b128 v[162:165], v144 offset:18528
	ds_read_b128 v[166:169], v144 offset:18560
	ds_read_b128 v[170:173], v144 offset:18592
	ds_read_b128 v[174:177], v144 offset:18624
	ds_read_b128 v[178:181], v144 offset:18656
	s_waitcnt lgkmcnt(10)
	v_mfma_f32_32x32x16_bf16 v[0:15], v[132:135], v[36:39], v[0:15]
	s_waitcnt lgkmcnt(8)
	v_mfma_f32_32x32x16_bf16 v[0:15], v[136:139], v[40:43], v[0:15]
	s_nop 8
	s_waitcnt lgkmcnt(7)
	v_mul_f32_e64 v16, v16, v148
	v_mul_f32_e64 v17, v17, v149
	v_pk_mul_f32 v[18:19], v[18:19], v[150:151]
	s_waitcnt lgkmcnt(6)
	v_pk_mul_f32 v[20:21], v[20:21], v[152:153]
	v_pk_mul_f32 v[22:23], v[22:23], v[154:155]
	s_waitcnt lgkmcnt(5)
	v_pk_mul_f32 v[24:25], v[24:25], v[156:157]
	v_pk_mul_f32 v[26:27], v[26:27], v[158:159]
	s_waitcnt lgkmcnt(4)
	v_pk_mul_f32 v[28:29], v[28:29], v[162:163]
	v_pk_mul_f32 v[96:97], v[30:31], v[164:165]
	s_waitcnt lgkmcnt(3)
	v_pk_mul_f32 v[0:1], v[0:1], v[166:167]
	v_pk_mul_f32 v[2:3], v[2:3], v[168:169]
	s_waitcnt lgkmcnt(2)
	v_pk_mul_f32 v[4:5], v[4:5], v[170:171]
	v_pk_mul_f32 v[6:7], v[6:7], v[172:173]
	s_waitcnt lgkmcnt(1)
	v_pk_mul_f32 v[8:9], v[8:9], v[174:175]
	v_pk_mul_f32 v[10:11], v[10:11], v[176:177]
	s_waitcnt lgkmcnt(0)
	s_barrier
	ds_read_b128 v[74:77], v106 offset:50176
	ds_read_b128 v[38:41], v106 offset:50192
	ds_read_b128 v[118:121], v107 offset:16896
	ds_read_b128 v[42:45], v107 offset:16912
	v_pk_mul_f32 v[98:99], v[14:15], v[180:181]
	v_mbcnt_lo_u32_b32 v14, -1, 0
	v_mbcnt_hi_u32_b32 v14, -1, v14
	v_pk_mul_f32 v[12:13], v[12:13], v[178:179]
	v_lshlrev_b32_e32 v14, 2, v14
	v_xor_b32_e32 v117, 4, v14
	v_mbcnt_lo_u32_b32 v14, -1, 0
	v_mbcnt_hi_u32_b32 v14, -1, v14
	s_waitcnt lgkmcnt(0)
	v_pk_add_f32 v[38:39], v[38:39], v[42:43]
	v_lshlrev_b32_e32 v14, 2, v14
	v_xor_b32_e32 v122, 8, v14
	v_mbcnt_lo_u32_b32 v14, -1, 0
	v_mbcnt_hi_u32_b32 v14, -1, v14
	v_lshlrev_b32_e32 v42, 16, v70
	v_lshlrev_b32_e32 v14, 2, v14
	v_xor_b32_e32 v123, 16, v14
	v_mbcnt_lo_u32_b32 v14, -1, 0
	v_mbcnt_hi_u32_b32 v14, -1, v14
	v_and_b32_e32 v43, 0xffff0000, v70
	v_lshlrev_b32_e32 v14, 2, v14
	v_xor_b32_e32 v124, 32, v14
	v_pk_add_f32 v[14:15], v[40:41], v[44:45]
	v_mul_f32_e32 v40, 0xbfb8aa3b, v42
	v_mul_f32_e32 v41, 0xbfb8aa3b, v43
	v_exp_f32_e32 v40, v40
	v_exp_f32_e32 v41, v41
	global_load_dwordx4 v[30:33], v[90:91], off offset:16
	global_load_dwordx4 v[34:37], v[90:91], off
	v_pk_mul_f32 v[72:73], v[38:39], v[38:39]
	v_pk_mul_f32 v[46:47], v[14:15], v[14:15]
	v_pk_add_f32 v[40:41], v[40:41], 1.0 op_sel_hi:[1,0]
	s_nop 0
	v_div_scale_f32 v44, s[36:37], v41, v41, v43
	v_rcp_f32_e32 v45, v44
	s_nop 0
	v_fma_f32 v70, -v44, v45, 1.0
	v_fmac_f32_e32 v45, v70, v45
	v_div_scale_f32 v70, vcc, v43, v41, v43
	v_mul_f32_e32 v71, v70, v45
	v_fma_f32 v125, -v44, v71, v70
	v_fmac_f32_e32 v71, v125, v45
	v_fma_f32 v44, -v44, v71, v70
	v_div_fmas_f32 v44, v44, v45, v71
	v_div_fixup_f32 v41, v44, v41, v43
	v_div_scale_f32 v43, s[36:37], v40, v40, v42
	v_rcp_f32_e32 v44, v43
	s_nop 0
	v_fma_f32 v45, -v43, v44, 1.0
	v_fmac_f32_e32 v44, v45, v44
	v_div_scale_f32 v45, vcc, v42, v40, v42
	v_mul_f32_e32 v70, v45, v44
	v_fma_f32 v71, -v43, v70, v45
	v_fmac_f32_e32 v70, v71, v44
	v_fma_f32 v43, -v43, v70, v45
	v_div_fmas_f32 v43, v43, v44, v70
	v_pk_add_f32 v[44:45], v[74:75], v[118:119]
	v_lshlrev_b32_e32 v118, 16, v69
	v_and_b32_e32 v69, 0xffff0000, v69
	v_mul_f32_e32 v70, 0xbfb8aa3b, v118
	v_mul_f32_e32 v71, 0xbfb8aa3b, v69
	v_exp_f32_e32 v70, v70
	v_exp_f32_e32 v71, v71
	v_div_fixup_f32 v40, v43, v40, v42
	v_pk_add_f32 v[42:43], v[76:77], v[120:121]
	v_pk_mul_f32 v[76:77], v[44:45], v[44:45]
	v_pk_add_f32 v[70:71], v[70:71], 1.0 op_sel_hi:[1,0]
	v_pk_mul_f32 v[74:75], v[42:43], v[42:43]
	v_div_scale_f32 v119, s[36:37], v71, v71, v69
	v_rcp_f32_e32 v120, v119
	v_add_f32_e32 v76, v76, v77
	v_add_f32_e32 v74, v74, v76
	v_add_f32_e32 v74, v75, v74
	v_fma_f32 v121, -v119, v120, 1.0
	v_fmac_f32_e32 v120, v121, v120
	v_div_scale_f32 v121, vcc, v69, v71, v69
	v_mul_f32_e32 v125, v121, v120
	v_fma_f32 v126, -v119, v125, v121
	v_fmac_f32_e32 v125, v126, v120
	v_fma_f32 v119, -v119, v125, v121
	v_div_fmas_f32 v119, v119, v120, v125
	v_div_fixup_f32 v71, v119, v71, v69
	v_div_scale_f32 v69, s[36:37], v70, v70, v118
	v_rcp_f32_e32 v119, v69
	v_add_f32_e32 v72, v72, v74
	v_add_f32_e32 v72, v73, v72
	v_add_f32_e32 v46, v46, v72
	v_fma_f32 v120, -v69, v119, 1.0
	v_fmac_f32_e32 v119, v120, v119
	v_div_scale_f32 v120, vcc, v118, v70, v118
	v_mul_f32_e32 v121, v120, v119
	v_fma_f32 v125, -v69, v121, v120
	v_fmac_f32_e32 v121, v125, v119
	v_fma_f32 v69, -v69, v121, v120
	v_div_fmas_f32 v69, v69, v119, v121
	v_div_fixup_f32 v70, v69, v70, v118
	v_lshlrev_b32_e32 v118, 16, v68
	v_and_b32_e32 v119, 0xffff0000, v68
	v_mul_f32_e32 v68, 0xbfb8aa3b, v118
	v_mul_f32_e32 v69, 0xbfb8aa3b, v119
	v_exp_f32_e32 v68, v68
	v_exp_f32_e32 v69, v69
	v_add_f32_e32 v46, v47, v46
	ds_bpermute_b32 v47, v117, v46
	v_pk_add_f32 v[68:69], v[68:69], 1.0 op_sel_hi:[1,0]
	s_nop 0
	v_div_scale_f32 v120, s[36:37], v69, v69, v119
	v_rcp_f32_e32 v121, v120
	s_waitcnt lgkmcnt(0)
	v_add_f32_e32 v46, v46, v47
	ds_bpermute_b32 v47, v122, v46
	v_fma_f32 v125, -v120, v121, 1.0
	v_fmac_f32_e32 v121, v125, v121
	v_div_scale_f32 v125, vcc, v119, v69, v119
	v_mul_f32_e32 v126, v125, v121
	v_fma_f32 v127, -v120, v126, v125
	v_fmac_f32_e32 v126, v127, v121
	s_waitcnt lgkmcnt(0)
	v_add_f32_e32 v46, v46, v47
	v_fma_f32 v120, -v120, v126, v125
	ds_bpermute_b32 v47, v123, v46
	v_div_fmas_f32 v120, v120, v121, v126
	v_div_fixup_f32 v69, v120, v69, v119
	v_div_scale_f32 v119, s[36:37], v68, v68, v118
	v_rcp_f32_e32 v120, v119
	s_waitcnt lgkmcnt(0)
	v_add_f32_e32 v46, v46, v47
	ds_bpermute_b32 v47, v124, v46
	v_fma_f32 v121, -v119, v120, 1.0
	v_fmac_f32_e32 v120, v121, v120
	v_div_scale_f32 v121, vcc, v118, v68, v118
	v_mul_f32_e32 v125, v121, v120
	v_fma_f32 v126, -v119, v125, v121
	v_fmac_f32_e32 v125, v126, v120
	s_waitcnt lgkmcnt(0)
	v_add_f32_e32 v46, v46, v47
	v_fma_f32 v119, -v119, v125, v121
	v_fmamk_f32 v46, v46, 0x3c000000, v192
	v_div_fmas_f32 v119, v119, v120, v125
	v_cmp_gt_f32_e32 vcc, s97, v46
	v_mul_f32_e32 v47, 0x4f800000, v46
	v_div_fixup_f32 v68, v119, v68, v118
	v_cndmask_b32_e32 v46, v46, v47, vcc
	v_sqrt_f32_e32 v47, v46
	s_nop 0
	v_add_u32_e32 v72, -1, v47
	v_fma_f32 v73, -v72, v47, v46
	v_cmp_ge_f32_e64 s[76:77], 0, v73
	v_add_u32_e32 v73, 1, v47
	s_nop 0
	v_cndmask_b32_e64 v72, v47, v72, s[76:77]
	v_fma_f32 v47, -v73, v47, v46
	v_cmp_lt_f32_e64 s[76:77], 0, v47
	s_nop 1
	v_cndmask_b32_e64 v47, v72, v73, s[76:77]
	v_mul_f32_e32 v72, 0x37800000, v47
	v_cndmask_b32_e32 v47, v47, v72, vcc
	v_cmp_class_f32_e32 vcc, v46, v248
	s_nop 1
	v_cndmask_b32_e32 v46, v47, v46, vcc
	v_div_scale_f32 v47, s[36:37], v46, v46, 1.0
	v_rcp_f32_e32 v72, v47
	s_nop 0
	v_fma_f32 v73, -v47, v72, 1.0
	v_fmac_f32_e32 v72, v73, v72
	v_div_scale_f32 v73, vcc, 1.0, v46, 1.0
	v_mul_f32_e32 v74, v73, v72
	v_fma_f32 v75, -v47, v74, v73
	v_fmac_f32_e32 v74, v75, v72
	v_fma_f32 v47, -v47, v74, v73
	v_div_fmas_f32 v47, v47, v72, v74
	v_div_fixup_f32 v46, v47, v46, 1.0
	v_pk_mul_f32 v[38:39], v[38:39], v[46:47] op_sel_hi:[1,0]
	v_pk_mul_f32 v[14:15], v[14:15], v[46:47] op_sel_hi:[1,0]
	s_waitcnt vmcnt(1)
	v_pk_mul_f32 v[30:31], v[30:31], v[38:39]
	v_pk_mul_f32 v[14:15], v[32:33], v[14:15]
	v_pk_mul_f32 v[38:39], v[40:41], v[30:31]
	v_mul_f32_e32 v30, 0xbfb8aa3b, v78
	v_mul_f32_e32 v31, 0xbfb8aa3b, v79
	v_exp_f32_e32 v30, v30
	v_exp_f32_e32 v31, v31
	v_pk_mul_f32 v[42:43], v[42:43], v[46:47] op_sel_hi:[1,0]
	v_pk_mul_f32 v[44:45], v[44:45], v[46:47] op_sel_hi:[1,0]
	s_waitcnt vmcnt(0)
	v_pk_mul_f32 v[36:37], v[36:37], v[42:43]
	v_pk_add_f32 v[30:31], v[30:31], 1.0 op_sel_hi:[1,0]
	v_pk_mul_f32 v[34:35], v[34:35], v[44:45]
	v_div_scale_f32 v32, s[36:37], v31, v31, v79
	v_rcp_f32_e32 v33, v32
	v_pk_mul_f32 v[34:35], v[68:69], v[34:35]
	v_pk_mul_f32 v[36:37], v[70:71], v[36:37]
	v_mov_b64_e32 v[44:45], v[48:49]
	v_fma_f32 v40, -v32, v33, 1.0
	v_fmac_f32_e32 v33, v40, v33
	v_div_scale_f32 v40, vcc, v79, v31, v79
	v_mul_f32_e32 v41, v40, v33
	v_fma_f32 v42, -v32, v41, v40
	v_fmac_f32_e32 v41, v42, v33
	v_fma_f32 v32, -v32, v41, v40
	v_div_fmas_f32 v32, v32, v33, v41
	v_div_fixup_f32 v31, v32, v31, v79
	v_div_scale_f32 v32, s[36:37], v30, v30, v78
	v_rcp_f32_e32 v33, v32
	v_mov_b64_e32 v[70:71], v[58:59]
	v_mov_b64_e32 v[46:47], v[50:51]
	v_mov_b64_e32 v[68:69], v[56:57]
	v_fma_f32 v40, -v32, v33, 1.0
	v_fmac_f32_e32 v33, v40, v33
	v_div_scale_f32 v40, vcc, v78, v30, v78
	v_mul_f32_e32 v41, v40, v33
	v_fma_f32 v42, -v32, v41, v40
	v_fmac_f32_e32 v41, v42, v33
	v_fma_f32 v32, -v32, v41, v40
	v_div_fmas_f32 v32, v32, v33, v41
	v_div_fixup_f32 v30, v32, v30, v78
	v_pk_mul_f32 v[14:15], v[30:31], v[14:15]
	v_cvt_pk_bf16_f32 v30, v34, v35
	v_cvt_pk_bf16_f32 v33, v14, v15
	v_lshlrev_b64 v[14:15], 11, v[94:95]
	v_cvt_pk_bf16_f32 v31, v36, v37
	v_cvt_pk_bf16_f32 v32, v38, v39
	v_lshl_add_u64 v[14:15], v[88:89], 0, v[14:15]
	global_store_dwordx4 v[14:15], v[30:33], off
	v_mov_b64_e32 v[40:41], v[64:65]
	v_mov_b64_e32 v[36:37], v[60:61]
	v_mov_b64_e32 v[32:33], v[52:53]
	v_mov_b64_e32 v[34:35], v[54:55]
	v_mov_b64_e32 v[42:43], v[66:67]
	v_mov_b64_e32 v[38:39], v[62:63]
	v_mov_b32_e32 v30, v96
	v_mov_b32_e32 v31, v97
	v_mov_b32_e32 v14, v98
	v_mov_b32_e32 v15, v99
	s_cbranch_scc0 .LBB0_982

.LBB0_991:
	s_or_b64 exec, exec, s[76:77]
	s_waitcnt lgkmcnt(1)
	v_mul_f32_e32 v117, 0x3fb8aa3b, v72
	v_exp_f32_e32 v117, v117
	s_and_saveexec_b64 s[36:37], s[40:41]
	ds_write_b32 v103, v117 offset:18432
	s_or_b64 exec, exec, s[36:37]
	v_mul_f32_e32 v118, 0x3fb8aa3b, v73
	v_exp_f32_e32 v118, v118
	s_and_saveexec_b64 s[36:37], s[40:41]
	ds_write_b32 v103, v118 offset:18436
	s_or_b64 exec, exec, s[36:37]
	v_mul_f32_e32 v119, 0x3fb8aa3b, v74
	v_exp_f32_e32 v119, v119
	s_and_saveexec_b64 s[36:37], s[40:41]
	ds_write_b32 v103, v119 offset:18440
	s_or_b64 exec, exec, s[36:37]
	v_mul_f32_e32 v120, 0x3fb8aa3b, v75
	v_exp_f32_e32 v120, v120
	s_and_saveexec_b64 s[36:37], s[40:41]
	ds_write_b32 v103, v120 offset:18444
	s_or_b64 exec, exec, s[36:37]
	s_waitcnt lgkmcnt(0)
	v_mul_f32_e32 v121, 0x3fb8aa3b, v76
	v_exp_f32_e32 v121, v121
	s_and_saveexec_b64 s[36:37], s[40:41]
	ds_write_b32 v103, v121 offset:18448
	s_or_b64 exec, exec, s[36:37]
	v_mul_f32_e32 v122, 0x3fb8aa3b, v77
	v_exp_f32_e32 v122, v122
	s_and_saveexec_b64 s[36:37], s[40:41]
	ds_write_b32 v103, v122 offset:18452
	s_or_b64 exec, exec, s[36:37]
	v_mul_f32_e32 v123, 0x3fb8aa3b, v78
	v_exp_f32_e32 v123, v123
	s_and_saveexec_b64 s[36:37], s[40:41]
	ds_write_b32 v103, v123 offset:18456
	s_or_b64 exec, exec, s[36:37]
	v_mul_f32_e32 v124, 0x3fb8aa3b, v79
	v_exp_f32_e32 v124, v124
	s_and_saveexec_b64 s[36:37], s[40:41]
	ds_write_b32 v103, v124 offset:18460
	s_or_b64 exec, exec, s[36:37]
	v_mul_f32_e32 v35, 0x3fb8aa3b, v35
	v_exp_f32_e32 v35, v35
	v_mul_f32_e32 v75, 0xbfb8aa3b, v75
	v_exp_f32_e32 v75, v75
	v_mul_f32_e32 v34, 0x3fb8aa3b, v34
	v_sub_f32_e32 v35, 1.0, v35
	v_exp_f32_e32 v34, v34
	v_mul_f32_e32 v75, v35, v75
	v_mul_f32_e32 v35, 0xbfb8aa3b, v74
	v_exp_f32_e32 v35, v35
	v_sub_f32_e32 v34, 1.0, v34
	v_mul_f32_e32 v33, 0x3fb8aa3b, v33
	v_exp_f32_e32 v33, v33
	v_mul_f32_e32 v74, v34, v35
	v_mul_f32_e32 v34, 0xbfb8aa3b, v73
	v_exp_f32_e32 v34, v34
	v_mul_f32_e32 v46, 0x3fb8aa3b, v46
	v_mul_f32_e32 v44, 0x3fb8aa3b, v44
	v_exp_f32_e32 v46, v46
	v_mul_f32_e32 v78, 0xbfb8aa3b, v78
	v_mul_f32_e32 v45, 0x3fb8aa3b, v45
	v_exp_f32_e32 v44, v44
	v_mul_f32_e32 v76, 0xbfb8aa3b, v76
	v_mul_f32_e32 v47, 0x3fb8aa3b, v47
	v_exp_f32_e32 v78, v78
	v_exp_f32_e32 v45, v45
	v_mul_f32_e32 v77, 0xbfb8aa3b, v77
	v_exp_f32_e32 v76, v76
	v_sub_f32_e32 v33, 1.0, v33
	v_mul_f32_e32 v32, 0x3fb8aa3b, v32
	v_exp_f32_e32 v47, v47
	v_mul_f32_e32 v79, 0xbfb8aa3b, v79
	v_exp_f32_e32 v77, v77
	v_mul_f32_e32 v73, v33, v34
	v_exp_f32_e32 v32, v32
	v_mul_f32_e32 v33, 0xbfb8aa3b, v72
	v_exp_f32_e32 v79, v79
	v_exp_f32_e32 v33, v33
	v_sub_f32_e32 v46, 1.0, v46
	v_sub_f32_e32 v44, 1.0, v44
	v_and_b32_e32 v125, 0xffff0000, v43
	v_lshlrev_b32_e32 v43, 16, v43
	v_mul_f32_e32 v46, v46, v78
	v_and_b32_e32 v78, 0xffff0000, v42
	v_sub_f32_e32 v45, 1.0, v45
	v_lshlrev_b32_e32 v42, 16, v42
	v_mul_f32_e32 v44, v44, v76
	v_and_b32_e32 v76, 0xffff0000, v41
	v_lshlrev_b32_e32 v41, 16, v41
	v_and_b32_e32 v35, 0xffff0000, v40
	v_lshlrev_b32_e32 v34, 16, v40
	v_mul_f32_e32 v124, v124, v125
	v_sub_f32_e32 v47, 1.0, v47
	v_mul_f32_e32 v43, v123, v43
	v_mul_f32_e32 v78, v122, v78
	v_mul_f32_e32 v45, v45, v77
	v_mul_f32_e32 v42, v121, v42
	v_mul_f32_e32 v76, v120, v76
	v_mul_f32_e32 v41, v119, v41
	v_mul_f32_e32 v35, v118, v35
	v_mul_f32_e32 v34, v117, v34
	v_sub_f32_e32 v32, 1.0, v32
	v_mul_f32_e32 v47, v47, v79
	v_mul_f32_e32 v40, v32, v33
	v_cvt_pk_bf16_f32 v32, v34, v35
	v_cvt_pk_bf16_f32 v33, v41, v76
	v_cvt_pk_bf16_f32 v34, v42, v78
	v_cvt_pk_bf16_f32 v35, v43, v124
	v_cvt_pk_bf16_f32 v42, v44, v45
	v_add_u32_e32 v44, v86, v82
	s_and_b64 vcc, exec, s[22:23]
	v_cvt_pk_bf16_f32 v40, v40, v73
	v_cvt_pk_bf16_f32 v41, v74, v75
	v_cvt_pk_bf16_f32 v43, v46, v47
	ds_write_b128 v44, v[32:35] offset:18944
	ds_write_b128 v108, v[40:43] offset:27648
	ds_write_b128 v108, v[36:39] offset:37888
	s_waitcnt lgkmcnt(0)
	s_barrier
	s_cbranch_vccz .LBB0_1009
	v_add_u32_e32 v117, v104, v105
	ds_read_b128 v[32:35], v109 offset:27648
	ds_read_b128 v[36:39], v117 offset:18944
	ds_read_b128 v[72:75], v109 offset:27680
	ds_read_b128 v[76:79], v117 offset:18976
	ds_read_b128 v[128:131], v109 offset:27712
	ds_read_b128 v[132:135], v117 offset:19008
	ds_read_b128 v[136:139], v109 offset:27744
	ds_read_b128 v[140:143], v117 offset:19040
	ds_read_b128 v[144:147], v109 offset:27776
	ds_read_b128 v[148:151], v117 offset:19072
	ds_read_b128 v[152:155], v109 offset:27808
	ds_read_b128 v[156:159], v117 offset:19104
	ds_read_b128 v[162:165], v109 offset:27840
	ds_read_b128 v[166:169], v117 offset:19136
	s_waitcnt lgkmcnt(12)
	v_mfma_f32_32x32x16_bf16 v[32:47], v[32:35], v[36:39], 0
	ds_read_b128 v[170:173], v109 offset:27872
	ds_read_b128 v[174:177], v117 offset:19168
	s_waitcnt lgkmcnt(12)
	v_mfma_f32_32x32x16_bf16 v[32:47], v[72:75], v[76:79], v[32:47]
	s_waitcnt lgkmcnt(10)
	v_mfma_f32_32x32x16_bf16 v[32:47], v[128:131], v[132:135], v[32:47]
	s_waitcnt lgkmcnt(8)
	v_mfma_f32_32x32x16_bf16 v[32:47], v[136:139], v[140:143], v[32:47]
	s_waitcnt lgkmcnt(6)
	v_mfma_f32_32x32x16_bf16 v[32:47], v[144:147], v[148:151], v[32:47]
	s_waitcnt lgkmcnt(4)
	v_mfma_f32_32x32x16_bf16 v[32:47], v[152:155], v[156:159], v[32:47]
	s_waitcnt lgkmcnt(2)
	v_mfma_f32_32x32x16_bf16 v[32:47], v[162:165], v[166:169], v[32:47]
	s_waitcnt lgkmcnt(0)
	v_mfma_f32_32x32x16_bf16 v[32:47], v[170:173], v[174:177], v[32:47]
	s_nop 11
	v_cndmask_b32_e64 v72, v32, 0, s[42:43]
	v_cndmask_b32_e64 v73, 0, v33, s[44:45]
	v_cndmask_b32_e64 v33, v34, 0, s[46:47]
	v_cndmask_b32_e64 v34, v35, 0, s[48:49]
	v_cndmask_b32_e64 v35, v36, 0, s[50:51]
	v_cndmask_b32_e64 v36, v37, 0, s[52:53]
	v_cndmask_b32_e64 v37, v38, 0, s[54:55]
	v_cndmask_b32_e64 v38, v39, 0, s[56:57]
	v_cndmask_b32_e64 v32, v72, v32, s[44:45]
	v_cndmask_b32_e64 v39, v40, 0, s[58:59]
	v_cndmask_b32_e64 v40, v41, 0, s[60:61]
	v_cndmask_b32_e64 v41, v42, 0, s[62:63]
	v_cndmask_b32_e64 v42, v43, 0, s[64:65]
	v_cndmask_b32_e64 v43, v44, 0, s[66:67]
	v_cndmask_b32_e64 v44, v45, 0, s[68:69]
	v_cndmask_b32_e64 v45, v46, 0, s[70:71]
	v_cndmask_b32_e64 v46, v47, 0, s[72:73]
	v_cvt_pk_bf16_f32 v33, v33, v34
	v_cvt_pk_bf16_f32 v34, v35, v36
	v_cvt_pk_bf16_f32 v35, v37, v38
	v_cvt_pk_bf16_f32 v32, v32, v73
	v_cvt_pk_bf16_f32 v36, v39, v40
	v_cvt_pk_bf16_f32 v37, v41, v42
	v_cvt_pk_bf16_f32 v38, v43, v44
	v_cvt_pk_bf16_f32 v39, v45, v46
	ds_write_b128 v116, v[32:35] offset:48128
	ds_write_b128 v116, v[36:39] offset:49152
.LBB0_1009:
	v_add_u32_e32 v117, 0x4800, v110
	ds_read2_b64 v[36:39], v117 offset0:64 offset1:66
	ds_read2_b64 v[72:75], v117 offset0:68 offset1:70
	ds_read2_b64 v[128:131], v117 offset0:72 offset1:74
	ds_read2_b64 v[132:135], v117 offset0:76 offset1:78
	v_cvt_pk_bf16_f32 v32, v16, v17
	v_cvt_pk_bf16_f32 v33, v18, v19
	v_cvt_pk_bf16_f32 v34, v20, v21
	v_cvt_pk_bf16_f32 v35, v22, v23
	v_cvt_pk_bf16_f32 v76, v24, v25
	v_cvt_pk_bf16_f32 v77, v26, v27
	v_cvt_pk_bf16_f32 v78, v28, v29
	v_cvt_pk_bf16_f32 v79, v96, v97
	v_cvt_pk_bf16_f32 v136, v0, v1
	v_cvt_pk_bf16_f32 v137, v2, v3
	v_cvt_pk_bf16_f32 v138, v4, v5
	v_cvt_pk_bf16_f32 v139, v6, v7
	v_cvt_pk_bf16_f32 v140, v8, v9
	v_cvt_pk_bf16_f32 v141, v10, v11
	v_cvt_pk_bf16_f32 v142, v12, v13
	v_cvt_pk_bf16_f32 v143, v98, v99
	s_andn2_b64 vcc, exec, s[24:25]
	s_waitcnt lgkmcnt(3)
	v_mfma_f32_32x32x16_bf16 v[32:47], v[32:35], v[36:39], 0
	s_waitcnt lgkmcnt(2)
	v_mfma_f32_32x32x16_bf16 v[32:47], v[76:79], v[72:75], v[32:47]
	s_waitcnt lgkmcnt(1)
	v_mfma_f32_32x32x16_bf16 v[32:47], v[136:139], v[128:131], v[32:47]
	s_waitcnt lgkmcnt(0)
	v_mfma_f32_32x32x16_bf16 v[32:47], v[140:143], v[132:135], v[32:47]
	s_barrier
	s_cbranch_vccnz .LBB0_984
	ds_read_b64_tr_b16 v[72:73], v111 offset:37888
	ds_read_b64_tr_b16 v[74:75], v111 offset:40448
	ds_read_b128 v[76:79], v116 offset:48128
	ds_read_b64_tr_b16 v[128:129], v111 offset:43008
	ds_read_b64_tr_b16 v[130:131], v111 offset:45568
	ds_read_b128 v[132:135], v116 offset:49152
	s_waitcnt lgkmcnt(3)
	v_mfma_f32_32x32x16_bf16 v[32:47], v[72:75], v[76:79], v[32:47]
	s_waitcnt lgkmcnt(0)
	v_mfma_f32_32x32x16_bf16 v[32:47], v[128:131], v[132:135], v[32:47]
	s_branch .LBB0_984

.LBB0_1021:
	v_mov_b64_e32 v[72:73], v[166:167]
	v_mov_b64_e32 v[74:75], v[164:165]
	v_mov_b64_e32 v[76:77], v[162:163]
	v_mov_b64_e32 v[78:79], v[158:159]
	s_mov_b32 s6, s55
	s_mov_b32 s7, 0
	s_cmp_lt_u32 s55, 61
	s_cbranch_scc0 .LBB0_1023
	s_lshl_b64 s[4:5], s[26:27], 1
	s_add_u32 s8, s4, s26
	s_addc_u32 s9, s5, s27
	v_lshl_add_u64 v[92:93], v[162:163], 0, v[160:161]
	v_lshl_add_u64 v[94:95], v[158:159], 0, v[160:161]
	global_load_dwordx4 v[64:67], v[92:93], off
	global_load_dwordx4 v[68:71], v[92:93], off offset:16
	global_load_dwordx4 v[72:75], v[94:95], off
	global_load_dwordx4 v[76:79], v[94:95], off offset:16
	v_lshl_add_u64 v[92:93], v[164:165], 0, v[160:161]
	v_lshl_add_u64 v[94:95], v[166:167], 0, v[160:161]
	global_load_dwordx4 v[80:83], v[92:93], off offset:-16
	global_load_dwordx4 v[84:87], v[92:93], off
	global_load_dwordx4 v[88:91], v[94:95], off
	global_load_dwordx4 v[92:95], v[94:95], off offset:16
	v_lshl_add_u64 v[124:125], v[162:163], 0, v[160:161]
	v_lshl_add_u64 v[124:125], v[124:125], 0, s[26:27]
	v_lshl_add_u64 v[126:127], v[158:159], 0, v[160:161]
	v_lshl_add_u64 v[126:127], v[126:127], 0, s[26:27]
	global_load_dwordx4 v[96:99], v[124:125], off
	global_load_dwordx4 v[100:103], v[124:125], off offset:16
	global_load_dwordx4 v[104:107], v[126:127], off
	global_load_dwordx4 v[108:111], v[126:127], off offset:16
	v_lshl_add_u64 v[124:125], v[164:165], 0, v[160:161]
	v_lshl_add_u64 v[124:125], v[124:125], 0, s[26:27]
	v_lshl_add_u64 v[126:127], v[166:167], 0, v[160:161]
	v_lshl_add_u64 v[126:127], v[126:127], 0, s[26:27]
	global_load_dwordx4 v[112:115], v[124:125], off offset:-16
	global_load_dwordx4 v[116:119], v[124:125], off
	global_load_dwordx4 v[120:123], v[126:127], off
	global_load_dwordx4 v[124:127], v[126:127], off offset:16
	s_waitcnt vmcnt(8)
	v_cvt_pk_bf16_f32 v64, v64, v65
	v_cvt_pk_bf16_f32 v65, v66, v67
	v_cvt_pk_bf16_f32 v66, v68, v69
	v_cvt_pk_bf16_f32 v67, v70, v71
	v_cvt_pk_bf16_f32 v68, v72, v73
	v_cvt_pk_bf16_f32 v69, v74, v75
	v_cvt_pk_bf16_f32 v70, v76, v77
	v_cvt_pk_bf16_f32 v71, v78, v79
	v_cvt_pk_bf16_f32 v72, v80, v81
	v_cvt_pk_bf16_f32 v73, v82, v83
	v_cvt_pk_bf16_f32 v74, v84, v85
	v_cvt_pk_bf16_f32 v75, v86, v87
	v_cvt_pk_bf16_f32 v76, v88, v89
	v_cvt_pk_bf16_f32 v77, v90, v91
	v_cvt_pk_bf16_f32 v78, v92, v93
	v_cvt_pk_bf16_f32 v79, v94, v95
	v_add_u32_e32 v80, 0x0, v212
	v_add_u32_e32 v81, 0x0, v215
	v_add_u32_e32 v82, 0x0, v213
	v_add_u32_e32 v83, 0x0, v214
	ds_write_b128 v80, v[64:67]
	ds_write_b128 v81, v[68:71]
	ds_write_b128 v82, v[72:75]
	ds_write_b128 v83, v[76:79]
	v_lshl_add_u64 v[92:93], v[162:163], 0, v[160:161]
	v_lshl_add_u64 v[92:93], v[92:93], 0, s[4:5]
	v_lshl_add_u64 v[94:95], v[158:159], 0, v[160:161]
	v_lshl_add_u64 v[94:95], v[94:95], 0, s[4:5]
	global_load_dwordx4 v[64:67], v[92:93], off
	global_load_dwordx4 v[68:71], v[92:93], off offset:16
	global_load_dwordx4 v[72:75], v[94:95], off
	global_load_dwordx4 v[76:79], v[94:95], off offset:16
	v_lshl_add_u64 v[92:93], v[164:165], 0, v[160:161]
	v_lshl_add_u64 v[92:93], v[92:93], 0, s[4:5]
	v_lshl_add_u64 v[94:95], v[166:167], 0, v[160:161]
	v_lshl_add_u64 v[94:95], v[94:95], 0, s[4:5]
	global_load_dwordx4 v[80:83], v[92:93], off offset:-16
	global_load_dwordx4 v[84:87], v[92:93], off
	global_load_dwordx4 v[88:91], v[94:95], off
	global_load_dwordx4 v[92:95], v[94:95], off offset:16
	s_waitcnt vmcnt(8)
	v_cvt_pk_bf16_f32 v96, v96, v97
	v_cvt_pk_bf16_f32 v97, v98, v99
	v_cvt_pk_bf16_f32 v98, v100, v101
	v_cvt_pk_bf16_f32 v99, v102, v103
	v_cvt_pk_bf16_f32 v100, v104, v105
	v_cvt_pk_bf16_f32 v101, v106, v107
	v_cvt_pk_bf16_f32 v102, v108, v109
	v_cvt_pk_bf16_f32 v103, v110, v111
	v_cvt_pk_bf16_f32 v104, v112, v113
	v_cvt_pk_bf16_f32 v105, v114, v115
	v_cvt_pk_bf16_f32 v106, v116, v117
	v_cvt_pk_bf16_f32 v107, v118, v119
	v_cvt_pk_bf16_f32 v108, v120, v121
	v_cvt_pk_bf16_f32 v109, v122, v123
	v_cvt_pk_bf16_f32 v110, v124, v125
	v_cvt_pk_bf16_f32 v111, v126, v127
	v_add_u32_e32 v112, 0x9400, v212
	v_add_u32_e32 v113, 0x9400, v215
	v_add_u32_e32 v114, 0x9400, v213
	v_add_u32_e32 v115, 0x9400, v214
	ds_write_b128 v112, v[96:99]
	ds_write_b128 v113, v[100:103]
	ds_write_b128 v114, v[104:107]
	ds_write_b128 v115, v[108:111]
	v_lshl_add_u64 v[124:125], v[162:163], 0, v[160:161]
	v_lshl_add_u64 v[124:125], v[124:125], 0, s[8:9]
	v_lshl_add_u64 v[126:127], v[158:159], 0, v[160:161]
	v_lshl_add_u64 v[126:127], v[126:127], 0, s[8:9]
	global_load_dwordx4 v[96:99], v[124:125], off
	global_load_dwordx4 v[100:103], v[124:125], off offset:16
	global_load_dwordx4 v[104:107], v[126:127], off
	global_load_dwordx4 v[108:111], v[126:127], off offset:16
	v_lshl_add_u64 v[124:125], v[164:165], 0, v[160:161]
	v_lshl_add_u64 v[124:125], v[124:125], 0, s[8:9]
	v_lshl_add_u64 v[126:127], v[166:167], 0, v[160:161]
	v_lshl_add_u64 v[126:127], v[126:127], 0, s[8:9]
	global_load_dwordx4 v[112:115], v[124:125], off offset:-16
	global_load_dwordx4 v[116:119], v[124:125], off
	global_load_dwordx4 v[120:123], v[126:127], off
	global_load_dwordx4 v[124:127], v[126:127], off offset:16
	s_waitcnt vmcnt(8)
	v_cvt_pk_bf16_f32 v64, v64, v65
	v_cvt_pk_bf16_f32 v65, v66, v67
	v_cvt_pk_bf16_f32 v66, v68, v69
	v_cvt_pk_bf16_f32 v67, v70, v71
	v_cvt_pk_bf16_f32 v68, v72, v73
	v_cvt_pk_bf16_f32 v69, v74, v75
	v_cvt_pk_bf16_f32 v70, v76, v77
	v_cvt_pk_bf16_f32 v71, v78, v79
	v_cvt_pk_bf16_f32 v72, v80, v81
	v_cvt_pk_bf16_f32 v73, v82, v83
	v_cvt_pk_bf16_f32 v74, v84, v85
	v_cvt_pk_bf16_f32 v75, v86, v87
	v_cvt_pk_bf16_f32 v76, v88, v89
	v_cvt_pk_bf16_f32 v77, v90, v91
	v_cvt_pk_bf16_f32 v78, v92, v93
	v_cvt_pk_bf16_f32 v79, v94, v95
	v_add_u32_e32 v80, 0x12800, v212
	v_add_u32_e32 v81, 0x12800, v215
	v_add_u32_e32 v82, 0x12800, v213
	v_add_u32_e32 v83, 0x12800, v214
	ds_write_b128 v80, v[64:67]
	ds_write_b128 v81, v[68:71]
	ds_write_b128 v82, v[72:75]
	ds_write_b128 v83, v[76:79]
	s_waitcnt vmcnt(0)
	v_cvt_pk_bf16_f32 v96, v96, v97
	v_cvt_pk_bf16_f32 v97, v98, v99
	v_cvt_pk_bf16_f32 v98, v100, v101
	v_cvt_pk_bf16_f32 v99, v102, v103
	v_cvt_pk_bf16_f32 v100, v104, v105
	v_cvt_pk_bf16_f32 v101, v106, v107
	v_cvt_pk_bf16_f32 v102, v108, v109
	v_cvt_pk_bf16_f32 v103, v110, v111
	v_cvt_pk_bf16_f32 v104, v112, v113
	v_cvt_pk_bf16_f32 v105, v114, v115
	v_cvt_pk_bf16_f32 v106, v116, v117
	v_cvt_pk_bf16_f32 v107, v118, v119
	v_cvt_pk_bf16_f32 v108, v120, v121
	v_cvt_pk_bf16_f32 v109, v122, v123
	v_cvt_pk_bf16_f32 v110, v124, v125
	v_cvt_pk_bf16_f32 v111, v126, v127
	v_add_u32_e32 v112, 0x1bc00, v212
	v_add_u32_e32 v113, 0x1bc00, v215
	v_add_u32_e32 v114, 0x1bc00, v213
	v_add_u32_e32 v115, 0x1bc00, v214
	ds_write_b128 v112, v[96:99]
	ds_write_b128 v113, v[100:103]
	ds_write_b128 v114, v[104:107]
	ds_write_b128 v115, v[108:111]
	s_branch .LBB0_1035
	s_branch .LBB0_1023

.LBB0_1365:
	s_add_u32 s89, s42, 0xde10000
	s_addc_u32 s90, s43, 0
	s_mul_i32 s22, s48, 0xb00000
	s_mul_hi_u32 s1, s48, 0xb00000
	s_add_u32 s22, s42, s22
	s_addc_u32 s1, s43, s1
	s_add_u32 s91, s22, 0x1b00000
	s_addc_u32 s52, s1, 0
	v_lshl_add_u64 v[0:1], v[0:1], 2, s[8:9]
	s_add_i32 m0, s94, 0x800
	v_mov_b32_e32 v7, 1
	global_load_lds_dword v[0:1], off
	v_add_u32_e32 v0, s0, v2
	v_ashrrev_i32_e32 v2, 31, v0
	v_lshrrev_b32_e32 v2, 26, v2
	v_lshlrev_b32_e32 v1, 4, v0
	v_add_u32_e32 v2, v0, v2
	v_bfe_i32 v0, v0, 27, 1
	v_lshrrev_b32_e32 v0, 22, v0
	v_add_u32_e32 v0, v1, v0
	v_and_b32_e32 v0, 0xfffffc00, v0
	v_sub_u32_e32 v0, v1, v0
	v_lshrrev_b32_e32 v3, 4, v0
	v_bitop3_b32 v0, v3, v0, 32 bitop3:0x6c
	v_ashrrev_i32_e32 v4, 31, v0
	v_ashrrev_i32_e32 v2, 6, v2
	v_lshrrev_b32_e32 v4, 26, v4
	v_lshlrev_b32_e32 v3, 3, v2
	v_add_u32_e32 v4, v0, v4
	v_and_b32_e32 v3, -16, v3
	v_ashrrev_i32_e32 v5, 6, v4
	v_and_b32_e32 v4, 0xc0, v4
	v_add_u32_e32 v3, v5, v3
	v_sub_u32_e32 v0, v0, v4
	v_lshlrev_b32_e32 v2, 5, v2
	v_ashrrev_i16_sdwa v0, v7, sext(v0) dst_sel:DWORD dst_unused:UNUSED_PAD src0_sel:DWORD src1_sel:BYTE_0
	v_lshlrev_b32_e32 v4, 1, v3
	v_lshrrev_b32_e32 v6, 2, v3
	v_and_b32_e32 v5, 3, v5
	v_and_b32_e32 v2, 32, v2
	v_bfe_i32 v0, v0, 0, 16
	v_and_b32_e32 v4, 24, v4
	v_and_b32_e32 v6, 4, v6
	v_and_or_b32 v5, v3, s2, v5
	v_or3_b32 v4, v5, v6, v4
	v_add_lshl_u32 v0, v2, v0, 1
	v_lshl_add_u32 v166, v3, 11, v0
	v_lshl_add_u32 v160, v4, 11, v0
	v_add_u32_e32 v0, 0x2000, v1
	v_ashrrev_i32_e32 v1, 31, v0
	v_lshrrev_b32_e32 v1, 22, v1
	v_add_u32_e32 v1, v0, v1
	v_ashrrev_i32_e32 v1, 10, v1
	v_mul_i32_i24_e32 v2, 0x400, v1
	v_sub_u32_e32 v0, v0, v2
	v_lshrrev_b32_e32 v2, 4, v0
	v_bitop3_b32 v0, v2, v0, 32 bitop3:0x6c
	v_ashrrev_i32_e32 v3, 31, v0
	v_lshrrev_b32_e32 v3, 26, v3
	v_lshlrev_b32_e32 v2, 3, v1
	v_add_u32_e32 v3, v0, v3
	v_and_b32_e32 v2, -16, v2
	v_ashrrev_i32_e32 v4, 6, v3
	v_and_b32_e32 v3, 0xc0, v3
	v_add_u32_e32 v2, v4, v2
	v_sub_u32_e32 v0, v0, v3
	v_lshlrev_b32_e32 v1, 5, v1
	v_ashrrev_i16_sdwa v0, v7, sext(v0) dst_sel:DWORD dst_unused:UNUSED_PAD src0_sel:DWORD src1_sel:BYTE_0
	v_lshlrev_b32_e32 v3, 1, v2
	v_lshrrev_b32_e32 v5, 2, v2
	v_and_b32_e32 v4, 3, v4
	v_and_b32_e32 v1, 32, v1
	v_bfe_i32 v0, v0, 0, 16
	v_and_b32_e32 v3, 24, v3
	v_and_b32_e32 v5, 4, v5
	v_and_or_b32 v4, v2, s2, v4
	v_or3_b32 v3, v4, v5, v3
	v_add_lshl_u32 v0, v1, v0, 1
	v_lshl_add_u32 v168, v2, 11, v0
	v_lshl_add_u32 v170, v3, 11, v0
	v_mbcnt_lo_u32_b32 v5, -1, 0
	v_mbcnt_hi_u32_b32 v5, -1, v5
	v_add_u32_e32 v5, s0, v5
	v_lshlrev_b32_e32 v5, 2, v5
	v_add_u32_e32 v5, 0x24000, v5
	ds_write_b32 v5, v166
	ds_write_b32 v5, v160 offset:2048
	ds_write_b32 v5, v168 offset:4096
	ds_write_b32 v5, v170 offset:6144
	s_ashr_i32 s53, s18, 8
	s_lshl_b32 s58, s39, 10
	s_ashr_i32 s55, s54, 31
	s_lshl_b64 s[8:9], s[56:57], 19
	s_lshl_b64 s[22:23], s[54:55], 19
	s_add_u32 s76, s91, s22
	s_addc_u32 s77, s52, s23
	s_add_i32 s55, s58, 0
	s_add_i32 m0, s55, 0x10000
	v_mov_b32_e32 v171, v161
	global_load_lds_dwordx4 v160, s[76:77]
	s_add_i32 m0, s55, 0x12000
	s_add_u32 s22, s76, 0x40000
	global_load_lds_dwordx4 v170, s[76:77]
	s_addc_u32 s23, s77, 0
	s_add_i32 m0, s55, 0x14000
	v_mov_b32_e32 v167, v161
	global_load_lds_dwordx4 v160, s[22:23]
	s_add_i32 m0, s55, 0x16000
	s_add_u32 s78, s89, s8
	s_addc_u32 s79, s90, s9
	s_add_i32 s59, s55, 0x2000
	global_load_lds_dwordx4 v170, s[22:23]
	s_mov_b32 m0, s55
	s_add_u32 s8, s78, 0x40000
	global_load_lds_dwordx4 v166, s[78:79]
	s_mov_b32 m0, s59
	s_addc_u32 s9, s79, 0
	s_add_i32 s1, s55, 0x4000
	global_load_lds_dwordx4 v168, s[78:79]
	s_mov_b32 m0, s1
	s_add_i32 s50, s55, 0x6000
	global_load_lds_dwordx4 v166, s[8:9]
	s_mov_b32 m0, s50
	s_cmp_eq_u32 s53, 1
	global_load_lds_dwordx4 v168, s[8:9]
	s_cselect_b64 s[8:9], -1, 0
	v_mov_b32_e32 v169, v161
	v_writelane_b32 v255, s8, 4
	v_lshl_add_u64 v[4:5], s[76:77], 0, v[160:161]
	v_lshl_add_u64 v[2:3], s[76:77], 0, v[170:171]
	v_lshl_add_u64 v[0:1], s[78:79], 0, v[166:167]
	v_writelane_b32 v255, s9, 5
	s_cmp_lg_u32 s53, 1
	v_lshl_add_u64 v[6:7], s[78:79], 0, v[168:169]
	s_cbranch_scc1 .LBB0_1367
	s_barrier

.LBB0_1368:
	v_add_u32_e32 v0, s0, v2
	v_lshlrev_b32_e32 v0, 2, v0
	v_add_u32_e32 v0, 0x24000, v0
	ds_read_b32 v166, v0
	ds_read_b32 v172, v0 offset:2048
	ds_read_b32 v168, v0 offset:4096
	ds_read_b32 v170, v0 offset:6144
	v_mov_b32_e32 v160, v161
	v_mov_b32_e32 v162, v161
	v_mov_b32_e32 v163, v161
	s_mov_b32 s66, s65
	s_mov_b64 s[78:79], s[6:7]
	s_mov_b64 s[76:77], s[84:85]
	s_mov_b32 s54, s72
	s_mov_b32 s56, s74

.LBB0_1376:
	s_waitcnt lgkmcnt(0)
	s_xor_b64 s[4:5], s[4:5], -1
	v_mov_b32_e32 v171, v161
	v_mov_b32_e32 v173, v161
	v_mov_b32_e32 v169, v161
	s_andn2_b64 vcc, exec, s[4:5]
	v_mov_b32_e32 v167, v161
	s_cbranch_vccnz .LBB0_1378
	s_mov_b32 s4, 0
	s_cbranch_execz .LBB0_1379
	s_branch .LBB0_1380
